# P7 prep: non-temporal (nt) hint on the read-once PROJC/PROJR stream loads
# baseline (speedup 1.0000x reference)
.LBB0_74:
	v_lshlrev_b32_e32 v49, 4, v37
	v_and_b32_e32 v40, 0x1ff0, v49
	v_mov_b32_e32 v181, v180
	v_cmp_ne_u32_e32 vcc, 0, v40
	v_mov_b64_e32 v[40:41], v[180:181]
	v_mov_b64_e32 v[42:43], v[180:181]
	v_mov_b64_e32 v[44:45], v[180:181]
	v_mov_b64_e32 v[46:47], v[180:181]
	s_and_saveexec_b64 s[36:37], vcc
	s_cbranch_execz .LBB0_76
	v_add_u32_e32 v40, -1, v49
	v_mad_i64_i32 v[44:45], s[8:9], v40, s26, v[24:25]
	global_load_dwordx4 v[40:43], v[44:45], off offset:1024 nt
	s_nop 0
	global_load_dwordx4 v[44:47], v[44:45], off offset:2048 nt
	s_waitcnt vmcnt(1)
	v_lshlrev_b32_e32 v50, 16, v40
	v_and_b32_e32 v51, 0xffff0000, v40
	s_waitcnt vmcnt(0)
	v_lshlrev_b32_e32 v52, 16, v44
	v_and_b32_e32 v53, 0xffff0000, v44
	v_lshlrev_b32_e32 v54, 16, v41
	v_and_b32_e32 v55, 0xffff0000, v41
	v_lshlrev_b32_e32 v44, 16, v45
	v_and_b32_e32 v45, 0xffff0000, v45
	v_lshlrev_b32_e32 v56, 16, v42
	v_and_b32_e32 v57, 0xffff0000, v42
	v_lshlrev_b32_e32 v58, 16, v46
	v_and_b32_e32 v59, 0xffff0000, v46
	v_lshlrev_b32_e32 v60, 16, v43
	v_and_b32_e32 v61, 0xffff0000, v43
	v_lshlrev_b32_e32 v46, 16, v47
	v_and_b32_e32 v47, 0xffff0000, v47
	v_pk_mul_f32 v[40:41], v[50:51], v[52:53]
	v_pk_mul_f32 v[42:43], v[54:55], v[44:45]
	v_pk_mul_f32 v[44:45], v[56:57], v[58:59]
	v_pk_mul_f32 v[46:47], v[60:61], v[46:47]
.LBB0_76:
	s_or_b64 exec, exec, s[36:37]
	v_mad_i64_i32 v[54:55], s[8:9], v49, s26, v[24:25]
	global_load_dwordx4 v[50:53], v[54:55], off offset:1024 nt
	s_nop 0
	global_load_dwordx4 v[54:57], v[54:55], off offset:2048 nt
	v_and_b32_e32 v49, 0x1ff0, v29
	s_mov_b32 s7, 0
	s_waitcnt vmcnt(1)
	v_lshlrev_b32_e32 v58, 16, v50
	v_and_b32_e32 v59, 0xffff0000, v50
	s_waitcnt vmcnt(0)
	v_lshlrev_b32_e32 v60, 16, v54
	v_and_b32_e32 v61, 0xffff0000, v54
	v_lshlrev_b32_e32 v50, 16, v51
	v_and_b32_e32 v51, 0xffff0000, v51
	v_lshlrev_b32_e32 v54, 16, v55
	v_and_b32_e32 v55, 0xffff0000, v55
	v_lshlrev_b32_e32 v62, 16, v52
	v_and_b32_e32 v63, 0xffff0000, v52
	v_lshlrev_b32_e32 v64, 16, v56
	v_and_b32_e32 v65, 0xffff0000, v56
	v_lshlrev_b32_e32 v66, 16, v53
	v_and_b32_e32 v67, 0xffff0000, v53
	v_lshlrev_b32_e32 v72, 16, v57
	v_and_b32_e32 v73, 0xffff0000, v57
	v_pk_mul_f32 v[52:53], v[58:59], v[60:61]
	v_pk_mul_f32 v[54:55], v[50:51], v[54:55]
	v_pk_mul_f32 v[56:57], v[62:63], v[64:65]
	v_pk_mul_f32 v[58:59], v[66:67], v[72:73]
	s_branch .LBB0_78

.LBB0_78:
	v_mov_b64_e32 v[64:65], v[52:53]
	v_add_u32_e32 v52, s7, v49
	v_mov_b32_e32 v181, v180
	v_mov_b64_e32 v[50:51], v[58:59]
	v_mov_b64_e32 v[60:61], v[56:57]
	v_mov_b64_e32 v[62:63], v[54:55]
	v_add_u32_e32 v66, s7, v29
	v_mad_i64_i32 v[96:97], s[8:9], v66, s26, v[24:25]
	global_load_dwordx4 v[92:95], v[96:97], off nt
	v_cmp_gt_u32_e32 vcc, s3, v52
	v_mov_b64_e32 v[52:53], v[180:181]
	v_mov_b64_e32 v[54:55], v[180:181]
	v_mov_b64_e32 v[56:57], v[180:181]
	v_mov_b64_e32 v[58:59], v[180:181]
	s_and_saveexec_b64 s[36:37], vcc
	s_cbranch_execz .LBB0_77
	v_add_u32_e32 v52, 1, v66
	v_mad_i64_i32 v[56:57], s[8:9], v52, s26, v[24:25]
	global_load_dwordx4 v[52:55], v[56:57], off offset:1024 nt
	s_nop 0
	global_load_dwordx4 v[56:59], v[56:57], off offset:2048 nt
	s_waitcnt vmcnt(1)
	v_lshlrev_b32_e32 v72, 16, v52
	v_and_b32_e32 v73, 0xffff0000, v52
	s_waitcnt vmcnt(0)
	v_lshlrev_b32_e32 v74, 16, v56
	v_and_b32_e32 v75, 0xffff0000, v56
	v_lshlrev_b32_e32 v76, 16, v53
	v_and_b32_e32 v77, 0xffff0000, v53
	v_lshlrev_b32_e32 v56, 16, v57
	v_and_b32_e32 v57, 0xffff0000, v57
	v_lshlrev_b32_e32 v78, 16, v54
	v_and_b32_e32 v79, 0xffff0000, v54
	v_lshlrev_b32_e32 v80, 16, v58
	v_and_b32_e32 v81, 0xffff0000, v58
	v_lshlrev_b32_e32 v82, 16, v55
	v_and_b32_e32 v83, 0xffff0000, v55
	v_lshlrev_b32_e32 v58, 16, v59
	v_and_b32_e32 v59, 0xffff0000, v59
	v_pk_mul_f32 v[52:53], v[72:73], v[74:75]
	v_pk_mul_f32 v[54:55], v[76:77], v[56:57]
	v_pk_mul_f32 v[56:57], v[78:79], v[80:81]
	v_pk_mul_f32 v[58:59], v[82:83], v[58:59]
	s_branch .LBB0_77
.LBB0_80:
	s_or_b64 exec, exec, s[28:29]
	s_and_saveexec_b64 s[28:29], s[0:1]
	s_cbranch_execz .LBB0_89
	v_readlane_b32 s48, v241, 0
	v_mov_b32_e32 v29, v180
	v_readlane_b32 s56, v241, 8
	v_readlane_b32 s57, v241, 9
	s_mov_b64 s[0:1], 0x1000
	v_lshlrev_b32_e32 v30, 4, v70
	v_lshl_add_u64 v[8:9], s[56:57], 0, v[28:29]
	v_lshl_add_u64 v[12:13], v[8:9], 0, s[0:1]
	s_movk_i32 s0, 0x1000
	v_add_co_u32_e32 v8, vcc, s0, v8
	v_mov_b32_e32 v31, v180
	v_readlane_b32 s60, v241, 12
	v_readlane_b32 s61, v241, 13
	v_readlane_b32 s62, v241, 14
	v_readlane_b32 s63, v241, 15
	v_addc_co_u32_e32 v9, vcc, 0, v9, vcc
	v_lshl_add_u64 v[30:31], s[56:57], 0, v[30:31]
	s_mov_b64 s[6:7], s[66:67]
	s_mov_b64 s[8:9], s[68:69]
	v_readlane_b32 s60, v241, 16
	v_add_co_u32_e32 v32, vcc, s0, v30
	global_load_dwordx4 v[0:3], v28, s[56:57] offset:16
	global_load_dwordx4 v[4:7], v28, s[56:57] offset:2048
	s_nop 0
	global_load_dwordx4 v[8:11], v[8:9], off nt
	s_nop 0
	global_load_dwordx4 v[12:15], v[12:13], off offset:16 nt
	s_nop 0
	global_load_dwordx4 v[16:19], v28, s[56:57] offset:2064
	v_readlane_b32 s64, v241, 20
	v_readlane_b32 s65, v241, 21
	v_addc_co_u32_e32 v33, vcc, 0, v31, vcc
	s_nop 3
	global_load_dwordx4 v[20:23], v28, s[64:65]
	global_load_dwordx4 v[24:27], v28, s[64:65] offset:16
	v_cmp_lt_i32_e32 vcc, v234, v228
	global_load_dwordx4 v[28:31], v28, s[56:57]
	v_readlane_b32 s0, v243, 7
	global_load_dwordx4 v[32:35], v[32:33], off offset:2048 nt
	v_cndmask_b32_e32 v37, v227, v234, vcc
	v_cmp_lt_i32_e32 vcc, v233, v228
	s_waitcnt vmcnt(14)
	v_lshlrev_b32_e32 v39, 2, v37
	v_readlane_b32 s1, v243, 8
	v_cndmask_b32_e32 v37, v227, v233, vcc
	v_cmp_lt_i32_e32 vcc, v232, v228
	v_lshlrev_b32_e32 v66, 2, v37
	v_readlane_b32 s49, v241, 1
	v_cndmask_b32_e32 v37, v227, v232, vcc
	v_lshlrev_b32_e32 v67, 2, v37
	v_mov_b32_e32 v37, v180
	s_waitcnt vmcnt(11)
	v_lshl_add_u64 v[44:45], s[0:1], 0, v[36:37]
	v_readlane_b32 s0, v243, 17
	v_readlane_b32 s1, v243, 18
	v_readlane_b32 s50, v241, 2
	v_readlane_b32 s51, v241, 3
	v_readlane_b32 s52, v241, 4
	v_readlane_b32 s53, v241, 5
	v_readlane_b32 s54, v241, 6
	v_readlane_b32 s55, v241, 7
	v_readlane_b32 s58, v241, 10
	v_readlane_b32 s59, v241, 11
	v_readlane_b32 s61, v241, 17
	v_readlane_b32 s62, v241, 18
	v_readlane_b32 s63, v241, 19
	s_waitcnt vmcnt(10)
	v_lshl_add_u64 v[46:47], s[0:1], 0, v[36:37]
	v_readlane_b32 s0, v243, 25
	v_readlane_b32 s66, v241, 22
	v_readlane_b32 s67, v241, 23
	v_readlane_b32 s68, v241, 24
	v_readlane_b32 s69, v241, 25
	v_readlane_b32 s48, v241, 48
	v_mov_b32_e32 v49, v180
	v_readlane_b32 s1, v243, 26
	s_mov_b64 s[68:69], s[8:9]
	s_mov_b64 s[66:67], s[6:7]
	v_readlane_b32 s49, v241, 49
	v_readlane_b32 s50, v241, 50
	v_readlane_b32 s51, v241, 51
	v_readlane_b32 s52, v241, 52
	v_readlane_b32 s53, v241, 53
	v_readlane_b32 s54, v241, 54
	v_readlane_b32 s55, v241, 55
	v_readlane_b32 s56, v241, 56
	v_readlane_b32 s57, v241, 57
	v_readlane_b32 s58, v241, 58
	v_readlane_b32 s59, v241, 59
	v_readlane_b32 s60, v241, 60
	v_readlane_b32 s61, v241, 61
	v_readlane_b32 s62, v241, 62
	v_readlane_b32 s63, v241, 63
	v_lshlrev_b32_e32 v38, 2, v70
	v_lshl_add_u64 v[40:41], s[44:45], 0, v[36:37]
	v_lshl_add_u64 v[42:43], s[46:47], 0, v[36:37]
	v_lshl_add_u64 v[48:49], s[0:1], 0, v[48:49]
	v_cmp_gt_u32_e32 vcc, 16, v70
	v_cmp_gt_u32_e64 s[38:39], 32, v70
	s_lshl_b32 s5, s5, 7
	s_mov_b64 s[34:35], 0
	v_readlane_b32 s70, v241, 26
	v_readlane_b32 s71, v241, 27
	v_readlane_b32 s72, v241, 28
	v_readlane_b32 s73, v241, 29
	v_readlane_b32 s74, v241, 30
	v_readlane_b32 s75, v241, 31
	s_branch .LBB0_83

.LBB0_83:
	v_lshlrev_b32_e32 v52, 4, v68
	v_and_b32_e32 v37, 0x1ff0, v52
	v_mov_b32_e32 v181, v180
	v_cmp_ne_u32_e64 s[0:1], 0, v37
	s_mov_b32 s6, 0
	v_mov_b32_e32 v97, 0
	v_lshlrev_b32_e32 v50, 1, v38
	v_mov_b32_e32 v100, 0
	v_mov_b32_e32 v104, 0
	v_mov_b32_e32 v106, 0
	v_mov_b32_e32 v99, 0
	v_mov_b32_e32 v103, 0
	v_mov_b32_e32 v107, 0
	v_mov_b32_e32 v111, 0
	v_mov_b32_e32 v65, 0
	v_mov_b32_e32 v83, 0
	v_mov_b32_e32 v91, 0
	v_mov_b32_e32 v102, 0
	v_mov_b32_e32 v105, 0
	v_mov_b32_e32 v108, 0
	v_mov_b32_e32 v113, 0
	v_mov_b32_e32 v118, 0
	v_mov_b32_e32 v70, 0
	v_mov_b32_e32 v71, 0
	v_mov_b32_e32 v72, 0
	v_mov_b32_e32 v109, 0
	v_mov_b32_e32 v101, 0
	v_mov_b32_e32 v98, 0
	v_mov_b64_e32 v[56:57], v[180:181]
	v_mov_b64_e32 v[58:59], v[180:181]
	v_mov_b32_e32 v73, 0
	v_mov_b32_e32 v119, 0
	s_and_saveexec_b64 s[36:37], s[0:1]
	s_cbranch_execz .LBB0_85
	v_add_u32_e32 v37, -1, v52
	v_mov_b64_e32 v[54:55], s[12:13]
	v_mad_i64_i32 v[54:55], s[0:1], v37, s95, v[54:55]
	v_mov_b32_e32 v37, v180
	s_waitcnt vmcnt(9)
	v_mov_b32_e32 v51, v180
	v_lshl_add_u64 v[56:57], v[54:55], 0, v[36:37]
	v_lshl_add_u64 v[54:55], v[54:55], 0, v[50:51]
	global_load_dwordx4 v[58:61], v[56:57], off nt
	global_load_dwordx4 v[62:65], v[56:57], off offset:1024 nt
	global_load_dwordx4 v[70:73], v[56:57], off offset:2048 nt
	s_waitcnt vmcnt(2)
	v_lshlrev_b32_e32 v106, 16, v58
	global_load_dwordx2 v[54:55], v[54:55], off offset:3072 nt
	v_and_b32_e32 v104, 0xffff0000, v58
	v_lshlrev_b32_e32 v100, 16, v59
	v_and_b32_e32 v97, 0xffff0000, v59
	v_and_b32_e32 v109, 0xffff0000, v60
	v_lshlrev_b32_e32 v101, 16, v61
	v_and_b32_e32 v98, 0xffff0000, v61
	s_waitcnt vmcnt(2)
	v_lshlrev_b32_e32 v111, 16, v62
	v_and_b32_e32 v107, 0xffff0000, v62
	v_lshlrev_b32_e32 v103, 16, v63
	v_and_b32_e32 v99, 0xffff0000, v63
	v_and_b32_e32 v59, 0xffff0000, v64
	v_lshlrev_b32_e32 v58, 16, v64
	v_and_b32_e32 v57, 0xffff0000, v65
	v_lshlrev_b32_e32 v56, 16, v65
	s_waitcnt vmcnt(1)
	v_lshlrev_b32_e32 v118, 16, v70
	v_and_b32_e32 v113, 0xffff0000, v70
	v_lshlrev_b32_e32 v108, 16, v71
	v_and_b32_e32 v105, 0xffff0000, v71
	v_lshlrev_b32_e32 v102, 16, v72
	v_and_b32_e32 v91, 0xffff0000, v72
	v_lshlrev_b32_e32 v83, 16, v73
	v_and_b32_e32 v65, 0xffff0000, v73
	v_lshlrev_b32_e32 v119, 16, v60
	s_waitcnt vmcnt(0)
	v_lshlrev_b32_e32 v73, 16, v54
	v_and_b32_e32 v72, 0xffff0000, v54
	v_lshlrev_b32_e32 v71, 16, v55
	v_and_b32_e32 v70, 0xffff0000, v55
.LBB0_85:
	s_or_b64 exec, exec, s[36:37]
	v_mov_b64_e32 v[54:55], s[12:13]
	v_mad_i64_i32 v[60:61], s[0:1], v52, s95, v[54:55]
	v_mov_b32_e32 v37, v180
	s_waitcnt vmcnt(9)
	v_mov_b32_e32 v51, v180
	v_lshl_add_u64 v[62:63], v[60:61], 0, v[36:37]
	v_lshl_add_u64 v[60:61], v[60:61], 0, v[50:51]
	global_load_dwordx4 v[52:55], v[62:63], off nt
	global_load_dwordx4 v[84:87], v[62:63], off offset:1024 nt
	global_load_dwordx4 v[92:95], v[62:63], off offset:2048 nt
	global_load_dwordx2 v[114:115], v[60:61], off offset:3072 nt
	v_and_b32_e32 v74, 0x1ff0, v69
	s_waitcnt vmcnt(3)
	v_lshlrev_b32_e32 v75, 16, v52
	v_and_b32_e32 v76, 0xffff0000, v52
	v_lshlrev_b32_e32 v77, 16, v53
	v_and_b32_e32 v78, 0xffff0000, v53
	v_lshlrev_b32_e32 v37, 16, v54
	v_and_b32_e32 v51, 0xffff0000, v54
	v_lshlrev_b32_e32 v110, 16, v55
	v_and_b32_e32 v112, 0xffff0000, v55
	s_waitcnt vmcnt(2)
	v_lshlrev_b32_e32 v79, 16, v84
	v_and_b32_e32 v80, 0xffff0000, v84
	v_lshlrev_b32_e32 v81, 16, v85
	v_and_b32_e32 v82, 0xffff0000, v85
	v_and_b32_e32 v61, 0xffff0000, v86
	v_lshlrev_b32_e32 v60, 16, v86
	v_and_b32_e32 v63, 0xffff0000, v87
	v_lshlrev_b32_e32 v62, 16, v87
	s_waitcnt vmcnt(1)
	v_lshlrev_b32_e32 v84, 16, v92
	v_and_b32_e32 v85, 0xffff0000, v92
	v_lshlrev_b32_e32 v86, 16, v93
	v_and_b32_e32 v87, 0xffff0000, v93
	v_lshlrev_b32_e32 v88, 16, v94
	v_and_b32_e32 v89, 0xffff0000, v94
	v_lshlrev_b32_e32 v90, 16, v95
	v_and_b32_e32 v92, 0xffff0000, v95
	s_waitcnt vmcnt(0)
	v_lshlrev_b32_e32 v93, 16, v114
	v_and_b32_e32 v94, 0xffff0000, v114
	v_lshlrev_b32_e32 v95, 16, v115
	v_and_b32_e32 v96, 0xffff0000, v115
	s_branch .LBB0_87

.LBB0_87:
	v_mov_b32_e32 v117, v37
	v_add_u32_e32 v37, s6, v74
	v_mov_b32_e32 v181, v180
	v_mov_b64_e32 v[52:53], v[60:61]
	v_mov_b64_e32 v[54:55], v[62:63]
	v_mov_b32_e32 v116, v51
	v_mov_b32_e32 v115, v110
	v_mov_b32_e32 v114, v112
	v_add_u32_e32 v64, s6, v69
	v_cmp_gt_u32_e64 s[0:1], s3, v37
	v_mov_b32_e32 v122, 0
	v_mov_b32_e32 v123, 0
	v_mov_b32_e32 v121, 0
	v_mov_b32_e32 v120, 0
	v_mov_b32_e32 v133, 0
	v_mov_b32_e32 v131, 0
	v_mov_b32_e32 v130, 0
	v_mov_b32_e32 v129, 0
	v_mov_b32_e32 v127, 0
	v_mov_b32_e32 v126, 0
	v_mov_b32_e32 v125, 0
	v_mov_b32_e32 v124, 0
	v_mov_b32_e32 v138, 0
	v_mov_b32_e32 v137, 0
	v_mov_b32_e32 v135, 0
	v_mov_b32_e32 v134, 0
	v_mov_b64_e32 v[62:63], v[180:181]
	v_mov_b64_e32 v[60:61], v[180:181]
	v_mov_b32_e32 v128, 0
	v_mov_b32_e32 v132, 0
	v_mov_b32_e32 v136, 0
	v_mov_b32_e32 v139, 0
	v_mov_b32_e32 v37, 0
	v_mov_b32_e32 v51, 0
	v_mov_b32_e32 v110, 0
	v_mov_b32_e32 v112, 0
	s_and_saveexec_b64 s[36:37], s[0:1]
	s_cbranch_execz .LBB0_86
	v_add_u32_e32 v37, 1, v64
	v_mov_b64_e32 v[60:61], s[12:13]
	v_mad_i64_i32 v[120:121], s[0:1], v37, s95, v[60:61]
	v_mov_b32_e32 v37, v180
	v_mov_b32_e32 v51, v180
	v_lshl_add_u64 v[122:123], v[120:121], 0, v[36:37]
	v_lshl_add_u64 v[120:121], v[120:121], 0, v[50:51]
	global_load_dwordx4 v[60:63], v[122:123], off nt
	global_load_dwordx4 v[124:127], v[122:123], off offset:1024 nt
	global_load_dwordx4 v[140:143], v[122:123], off offset:2048 nt
	global_load_dwordx2 v[144:145], v[120:121], off offset:3072 nt
	s_waitcnt vmcnt(3)
	v_lshlrev_b32_e32 v128, 16, v60
	v_and_b32_e32 v132, 0xffff0000, v60
	v_lshlrev_b32_e32 v136, 16, v61
	v_and_b32_e32 v139, 0xffff0000, v61
	v_lshlrev_b32_e32 v37, 16, v62
	v_and_b32_e32 v51, 0xffff0000, v62
	v_lshlrev_b32_e32 v110, 16, v63
	v_and_b32_e32 v112, 0xffff0000, v63
	s_waitcnt vmcnt(2)
	v_lshlrev_b32_e32 v120, 16, v124
	v_and_b32_e32 v121, 0xffff0000, v124
	v_lshlrev_b32_e32 v123, 16, v125
	v_and_b32_e32 v122, 0xffff0000, v125
	v_and_b32_e32 v61, 0xffff0000, v126
	v_lshlrev_b32_e32 v60, 16, v126
	v_and_b32_e32 v63, 0xffff0000, v127
	v_lshlrev_b32_e32 v62, 16, v127
	s_waitcnt vmcnt(1)
	v_lshlrev_b32_e32 v124, 16, v140
	v_and_b32_e32 v125, 0xffff0000, v140
	v_lshlrev_b32_e32 v126, 16, v141
	v_and_b32_e32 v127, 0xffff0000, v141
	v_lshlrev_b32_e32 v129, 16, v142
	v_and_b32_e32 v130, 0xffff0000, v142
	v_lshlrev_b32_e32 v131, 16, v143
	v_and_b32_e32 v133, 0xffff0000, v143
	s_waitcnt vmcnt(0)
	v_lshlrev_b32_e32 v134, 16, v144
	v_and_b32_e32 v135, 0xffff0000, v144
	v_lshlrev_b32_e32 v137, 16, v145
	v_and_b32_e32 v138, 0xffff0000, v145
	s_branch .LBB0_86
